# attention prologue: all independent global loads in one latency window (bias copy, Q, diagonal K, KN, CB[q]); cut biases read from LDS copy
# speedup vs baseline: 1.0019x; 1.0016x over previous
;   #define DMA_K(t,slot) glds16(ksrc+(long)TAU(t)*KVBLK*DM,(unsigned)__builtin_amdgcn_readfirstlane(kdst+(slot)))
;   #define DMA_V(t,slot) glds16(vsrc+(long)TAU(t)*KVBLK*DM,(unsigned)__builtin_amdgcn_readfirstlane(vdst+(slot)))
; template<int THRL> __device__ __forceinline__ void attn_unit(int b,int h,int qb,const bf16*Q,const bf16*__restrict__ K,const bf16*__restrict__ V,bf16*O,const bf16*GF,const float*CBh,const unsigned*KN,const unsigned*QN,char*shm){
;     ...
;   DMA_K(0,0);DMA_V(0,0);DMA_K(1,SLOTB);DMA_K(2,2*SLOTB);
;   { const int n4=(q0+QB)>>2; f32x4*dst=(f32x4*)(shm+LDS_BIAS); const f32x4*src=(const f32x4*)CBh;
;     for(int i=tid;i<n4;i+=NW*64)dst[i]=src[i]; }
;   bf16x8 qr[4];
;   #pragma unroll
;   for(int d0=0;d0<4;++d0)qr[d0]=*reinterpret_cast<const bf16x8*>(&Qw[(long)r32*DM+d0*16+hi*8]);
;   float umin;
;   { const bf16*Kd=K+(rowbase+q0+wid*QBLK)*DM+h*D; float ds=0.f,qq=0.f;
;     #pragma unroll
;     for(int d0=0;d0<4;++d0){ const bf16x8 kk=*reinterpret_cast<const bf16x8*>(&Kd[(long)r32*DM+d0*16+hi*8]);
;       #pragma unroll
;       for(int e=0;e<8;++e){ const float qf=__builtin_bit_cast(float,(unsigned)(unsigned short)qr[d0][e]<<16); ds+=qf*__builtin_bit_cast(float,(unsigned)(unsigned short)kk[e]<<16); qq+=qf*qf; } }
;     { auto rr=__builtin_amdgcn_permlane32_swap(__float_as_uint(ds),__float_as_uint(ds),false,false); ds=__uint_as_float(rr[0])+__uint_as_float(rr[1]); }
;     { auto rr=__builtin_amdgcn_permlane32_swap(__float_as_uint(qq),__float_as_uint(qq),false,false); qq=__uint_as_float(rr[0])+__uint_as_float(rr[1]); }
;     const float kmx=sqrtf(__uint_as_float(KN[0])+__uint_as_float(KN[1]));
;     float v=ds+CBh[q0+wid*QBLK+r32]-sqrtf(qq)*kmx*1.001f;
.LBB0_557:
	s_and_b64 vcc, exec, s[6:7]
	s_cbranch_vccz .LBB0_535
	s_ashr_i32 s48, s2, 5
	v_mov_b32_e32 v34, v236
	s_lshl_b32 s15, s48, 8
	s_and_b32 s51, s2, 31
	s_bfe_u32 s14, s2, 0x10004
	s_lshl_b32 s2, s2, 6
	v_readfirstlane_b32 s46, v34
	s_sub_i32 s42, 0x2000, s15
	s_ashr_i32 s67, s46, 6
	s_and_b32 s2, s2, 0x3c0
	s_lshr_b32 s68, s42, 6
	s_lshl_b32 s8, s14, 24
	s_add_u32 s6, s58, s8
	s_addc_u32 s7, s59, 0
	s_lshl_b32 s66, s2, 1
	s_add_u32 s6, s6, s66
	s_addc_u32 s7, s7, 0
	s_add_u32 s2, s60, s8
	v_and_b32_e32 v188, 63, v34
	s_addc_u32 s9, s61, 0
	s_add_u32 s8, s2, s66
	v_lshlrev_b32_e32 v0, 11, v188
	s_addc_u32 s9, s9, 0
	v_lshl_add_u64 v[2:3], s[6:7], 0, v[0:1]
	s_lshl_b32 s6, s67, 3
	s_lshl_b32 s2, s67, 4
	v_bfe_u32 v0, v34, 2, 4
	s_ashr_i32 s7, s6, 31
	v_and_or_b32 v0, s2, 48, v0
	s_ashr_i32 s2, s46, 3
	v_lshl_add_u64 v[182:183], s[6:7], 1, v[2:3]
	s_and_b32 s6, s2, 0xffffffe0
	s_ashr_i32 s7, s6, 31
	s_lshl_b32 s49, s67, 10
	v_lshlrev_b32_e32 v0, 11, v0
	v_lshlrev_b32_e32 v189, 3, v34
	s_cmp_lg_u32 0, -1
	v_lshl_add_u64 v[2:3], s[8:9], 0, v[0:1]
	v_and_b32_e32 v192, 24, v189
	s_cselect_b32 s2, 0, 0
	s_add_i32 s40, s68, -4
	s_mov_b32 s41, s19
	v_lshl_add_u64 v[2:3], s[6:7], 1, v[2:3]
	v_lshlrev_b32_e32 v0, 1, v192
	s_lshl_b64 s[6:7], s[40:41], 17
	v_lshl_add_u64 v[184:185], v[2:3], 0, v[0:1]
	s_add_i32 s69, s49, s2
	v_lshl_add_u64 v[2:3], v[182:183], 0, s[6:7]
	s_mov_b32 s2, m0
	s_mov_b32 m0, s69
	s_nop 0
	global_load_lds_dwordx4 v[2:3], off
	s_mov_b32 m0, s2
	s_add_i32 s18, s68, -3
	s_add_i32 s70, s69, 0x6000
	v_lshl_add_u64 v[2:3], v[184:185], 0, s[6:7]
	s_mov_b32 s2, m0
	s_mov_b32 m0, s70
	s_nop 0
	global_load_lds_dwordx4 v[2:3], off
	s_mov_b32 m0, s2
	s_lshl_b64 s[6:7], s[18:19], 17
	v_lshl_add_u64 v[2:3], v[182:183], 0, s[6:7]
	s_add_i32 s2, s69, 0x2000
	s_mov_b32 s6, m0
	s_mov_b32 m0, s2
	s_nop 0
	global_load_lds_dwordx4 v[2:3], off
	s_mov_b32 m0, s6
	s_add_i32 s6, s68, -2
	s_mov_b32 s7, s19
	s_lshl_b64 s[6:7], s[6:7], 17
	v_lshl_add_u64 v[2:3], v[182:183], 0, s[6:7]
	s_add_i32 s2, s69, 0x4000
	s_mov_b32 s6, m0
	s_mov_b32 m0, s2
	s_nop 0
	global_load_lds_dwordx4 v[2:3], off
	s_mov_b32 m0, s6
	s_lshr_b32 s2, s42, 2
	s_add_i32 s8, s94, s51
	s_mov_b32 s9, s19
	s_lshl_b64 s[8:9], s[8:9], 15
	s_add_u32 s8, s77, s8
	v_ashrrev_i32_e32 v35, 31, v34
	s_addc_u32 s9, s33, s9
	v_mov_b32_e32 v56, s2
	v_lshl_add_u32 v52, v34, 4, s89
	v_lshl_add_u64 v[54:55], v[34:35], 4, s[8:9]
	s_mov_b64 s[42:43], 0x2000
	v_cmp_gt_i32_e32 vcc, v56, v34
	s_and_b64 exec, exec, vcc
	global_load_dwordx4 v[36:39], v[54:55], off
	v_add_u32_e32 v53, 0x200, v34
	v_cmp_gt_i32_e32 vcc, v56, v53
	v_lshl_add_u64 v[54:55], v[54:55], 0, s[42:43]
	s_and_b64 exec, exec, vcc
	global_load_dwordx4 v[40:43], v[54:55], off
	v_add_u32_e32 v53, 0x400, v34
	v_cmp_gt_i32_e32 vcc, v56, v53
	v_lshl_add_u64 v[54:55], v[54:55], 0, s[42:43]
	s_and_b64 exec, exec, vcc
	global_load_dwordx4 v[44:47], v[54:55], off
	v_add_u32_e32 v53, 0x600, v34
	v_cmp_gt_i32_e32 vcc, v56, v53
	v_lshl_add_u64 v[54:55], v[54:55], 0, s[42:43]
	s_and_b64 exec, exec, vcc
	global_load_dwordx4 v[48:51], v[54:55], off
	s_mov_b64 exec, -1
	s_mov_b64 s[6:7], -1
.LBB0_561:
	s_or_b64 exec, exec, s[6:7]
	s_or_b32 s2, s51, s25
	s_lshl_b64 s[8:9], s[18:19], 16
	s_lshl_b32 s18, s2, 13
	s_lshl_b64 s[6:7], s[18:19], 2
	s_add_u32 s44, s77, s6
	s_addc_u32 s45, s33, s7
	s_lshl_b32 s18, s2, 1
	s_lshl_b64 s[6:7], s[18:19], 2
	s_add_u32 s6, s54, s6
	s_addc_u32 s7, s55, s7
	s_lshl_b32 s14, s14, 13
	s_sub_i32 s2, 0x1f00, s15
	s_lshl_b32 s41, s67, 5
	s_add_i32 s14, s2, s14
	s_ashr_i32 s15, s41, 31
	s_add_u32 s42, s41, s14
	s_addc_u32 s43, s15, 0
	s_lshl_b64 s[52:53], s[42:43], 11
	s_add_u32 s14, s56, s52
	s_addc_u32 s15, s57, s53
	s_add_u32 s14, s14, s66
	s_addc_u32 s15, s15, 0
	s_and_b32 s18, s46, 0x3fffffc0
	s_lshl_b32 s18, s18, 2
	s_add_i32 s50, s18, 0
	s_add_u32 s18, s58, s52
	v_and_b32_e32 v190, 31, v34
	s_addc_u32 s47, s59, s53
	v_lshrrev_b32_e32 v191, 5, v188
	v_lshlrev_b32_e32 v0, 11, v190
	s_add_u32 s46, s18, s66
	v_lshl_or_b32 v0, v191, 4, v0
	s_addc_u32 s47, s47, 0
	global_load_dwordx4 v[126:129], v0, s[14:15]
	global_load_dwordx4 v[122:125], v0, s[14:15] offset:32
	global_load_dwordx4 v[118:121], v0, s[14:15] offset:64
	global_load_dwordx4 v[114:117], v0, s[14:15] offset:96
	global_load_dwordx4 v[2:5], v0, s[46:47]
	s_add_i32 s2, s41, s2
	global_load_dwordx4 v[58:61], v0, s[46:47] offset:32
	global_load_dwordx4 v[62:65], v0, s[46:47] offset:64
	global_load_dwordx4 v[66:69], v0, s[46:47] offset:96
	global_load_dwordx2 v[70:71], v1, s[6:7]
	v_or_b32_e32 v74, s2, v190
	v_ashrrev_i32_e32 v75, 31, v74
	v_lshl_add_u64 v[74:75], v[74:75], 2, s[44:45]
	global_load_dword v72, v[74:75], off
	s_waitcnt vmcnt(9)
	v_cmp_gt_i32_e32 vcc, v56, v34
	s_and_b64 exec, exec, vcc
	ds_write_b128 v52, v[36:39]
	v_add_u32_e32 v53, 0x200, v34
	v_cmp_gt_i32_e32 vcc, v56, v53
	s_and_b64 exec, exec, vcc
	ds_write_b128 v52, v[40:43] offset:8192
	v_add_u32_e32 v53, 0x400, v34
	v_cmp_gt_i32_e32 vcc, v56, v53
	s_and_b64 exec, exec, vcc
	ds_write_b128 v52, v[44:47] offset:16384
	v_add_u32_e32 v53, 0x600, v34
	v_cmp_gt_i32_e32 vcc, v56, v53
	s_and_b64 exec, exec, vcc
	ds_write_b128 v52, v[48:51] offset:24576
	s_mov_b64 exec, -1
	v_lshlrev_b32_e32 v6, 16, v126
	v_and_b32_e32 v8, 0xffff0000, v126
	s_waitcnt vmcnt(5)
; template<int THRL> __device__ __forceinline__ void attn_unit(int b,int h,int qb,const bf16*Q,const bf16*__restrict__ K,const bf16*__restrict__ V,bf16*O,const bf16*GF,const float*CBh,const unsigned*KN,const unsigned*QN,char*shm){
;     ...
;   { const bf16*Kd=K+(rowbase+q0+wid*QBLK)*DM+h*D; float ds=0.f,qq=0.f;
;     #pragma unroll
;     for(int d0=0;d0<4;++d0){ const bf16x8 kk=*reinterpret_cast<const bf16x8*>(&Kd[(long)r32*DM+d0*16+hi*8]);
;       #pragma unroll
;       for(int e=0;e<8;++e){ const float qf=__builtin_bit_cast(float,(unsigned)(unsigned short)qr[d0][e]<<16); ds+=qf*__builtin_bit_cast(float,(unsigned)(unsigned short)kk[e]<<16); qq+=qf*qf; } }
;     { auto rr=__builtin_amdgcn_permlane32_swap(__float_as_uint(ds),__float_as_uint(ds),false,false); ds=__uint_as_float(rr[0])+__uint_as_float(rr[1]); }
;     { auto rr=__builtin_amdgcn_permlane32_swap(__float_as_uint(qq),__float_as_uint(qq),false,false); qq=__uint_as_float(rr[0])+__uint_as_float(rr[1]); }
;     const float kmx=sqrtf(__uint_as_float(KN[0])+__uint_as_float(KN[1]));
;     float v=ds+CBh[q0+wid*QBLK+r32]-sqrtf(qq)*kmx*1.001f;
;     #pragma unroll
;     for(int m=1;m<32;m<<=1)v=fminf(v,__builtin_bit_cast(float,__builtin_amdgcn_ds_bpermute((lane^m)<<2,__builtin_bit_cast(int,v))));
;     float*wmin=(float*)(shm+LDS_WS);
;     if(lane==0)wmin[wid*64]=v;
	v_lshlrev_b32_e32 v7, 16, v2
	v_fma_f32 v7, v6, v7, 0
	v_and_b32_e32 v2, 0xffff0000, v2
	v_fmac_f32_e32 v7, v8, v2
	v_mul_f32_e32 v8, v8, v8
	v_fmac_f32_e32 v8, v6, v6
	v_lshlrev_b32_e32 v2, 16, v127
	v_lshlrev_b32_e32 v6, 16, v3
	v_fmac_f32_e32 v7, v2, v6
	v_fmac_f32_e32 v8, v2, v2
	v_and_b32_e32 v2, 0xffff0000, v127
	v_and_b32_e32 v3, 0xffff0000, v3
	v_fmac_f32_e32 v7, v2, v3
	v_fmac_f32_e32 v8, v2, v2
	v_lshlrev_b32_e32 v2, 16, v128
	v_lshlrev_b32_e32 v3, 16, v4
	v_fmac_f32_e32 v7, v2, v3
	v_fmac_f32_e32 v8, v2, v2
	v_and_b32_e32 v2, 0xffff0000, v128
	v_and_b32_e32 v3, 0xffff0000, v4
	v_fmac_f32_e32 v7, v2, v3
	v_fmac_f32_e32 v8, v2, v2
	v_lshlrev_b32_e32 v2, 16, v129
	v_lshlrev_b32_e32 v3, 16, v5
	v_fmac_f32_e32 v7, v2, v3
	v_fmac_f32_e32 v8, v2, v2
	v_and_b32_e32 v2, 0xffff0000, v129
	v_and_b32_e32 v3, 0xffff0000, v5
	v_fmac_f32_e32 v7, v2, v3
	v_fmac_f32_e32 v8, v2, v2
	s_waitcnt vmcnt(4)
	v_mov_b32_e32 v2, v58
	v_mov_b32_e32 v3, v59
	v_mov_b32_e32 v4, v60
	v_mov_b32_e32 v5, v61
	v_lshlrev_b32_e32 v6, 16, v122
	v_fmac_f32_e32 v8, v6, v6
	v_lshlrev_b32_e32 v9, 16, v2
	v_fmac_f32_e32 v7, v6, v9
	v_and_b32_e32 v6, 0xffff0000, v122
	v_and_b32_e32 v2, 0xffff0000, v2
	v_fmac_f32_e32 v7, v6, v2
	v_fmac_f32_e32 v8, v6, v6
	v_lshlrev_b32_e32 v2, 16, v123
	v_lshlrev_b32_e32 v6, 16, v3
	v_fmac_f32_e32 v7, v2, v6
	v_fmac_f32_e32 v8, v2, v2
	v_and_b32_e32 v2, 0xffff0000, v123
	v_and_b32_e32 v3, 0xffff0000, v3
	v_fmac_f32_e32 v7, v2, v3
	v_fmac_f32_e32 v8, v2, v2
	v_lshlrev_b32_e32 v2, 16, v124
	v_lshlrev_b32_e32 v3, 16, v4
	v_fmac_f32_e32 v7, v2, v3
	v_fmac_f32_e32 v8, v2, v2
	v_and_b32_e32 v2, 0xffff0000, v124
	v_and_b32_e32 v3, 0xffff0000, v4
	v_fmac_f32_e32 v7, v2, v3
	v_fmac_f32_e32 v8, v2, v2
	v_lshlrev_b32_e32 v2, 16, v125
	v_lshlrev_b32_e32 v3, 16, v5
	v_fmac_f32_e32 v7, v2, v3
	v_fmac_f32_e32 v8, v2, v2
	v_and_b32_e32 v2, 0xffff0000, v125
	v_and_b32_e32 v3, 0xffff0000, v5
	v_fmac_f32_e32 v7, v2, v3
	v_fmac_f32_e32 v8, v2, v2
	s_waitcnt vmcnt(3)
	v_mov_b32_e32 v2, v62
	v_mov_b32_e32 v3, v63
	v_mov_b32_e32 v4, v64
	v_mov_b32_e32 v5, v65
	v_lshlrev_b32_e32 v6, 16, v118
	v_fmac_f32_e32 v8, v6, v6
	v_lshlrev_b32_e32 v9, 16, v2
	v_fmac_f32_e32 v7, v6, v9
	v_and_b32_e32 v6, 0xffff0000, v118
	v_and_b32_e32 v2, 0xffff0000, v2
	v_fmac_f32_e32 v7, v6, v2
	v_fmac_f32_e32 v8, v6, v6
	v_lshlrev_b32_e32 v2, 16, v119
	v_lshlrev_b32_e32 v6, 16, v3
	v_fmac_f32_e32 v7, v2, v6
	v_fmac_f32_e32 v8, v2, v2
	v_and_b32_e32 v2, 0xffff0000, v119
	v_and_b32_e32 v3, 0xffff0000, v3
	v_fmac_f32_e32 v7, v2, v3
	v_fmac_f32_e32 v8, v2, v2
	v_lshlrev_b32_e32 v2, 16, v120
	v_lshlrev_b32_e32 v3, 16, v4
	v_fmac_f32_e32 v7, v2, v3
	v_fmac_f32_e32 v8, v2, v2
	v_and_b32_e32 v2, 0xffff0000, v120
	v_and_b32_e32 v3, 0xffff0000, v4
	v_fmac_f32_e32 v7, v2, v3
	v_fmac_f32_e32 v8, v2, v2
	v_lshlrev_b32_e32 v2, 16, v121
	v_lshlrev_b32_e32 v3, 16, v5
	v_fmac_f32_e32 v7, v2, v3
	v_fmac_f32_e32 v8, v2, v2
	v_and_b32_e32 v2, 0xffff0000, v121
	v_and_b32_e32 v3, 0xffff0000, v5
	v_fmac_f32_e32 v7, v2, v3
	v_fmac_f32_e32 v8, v2, v2
	s_waitcnt vmcnt(2)
	v_mov_b32_e32 v2, v66
	v_mov_b32_e32 v3, v67
	v_mov_b32_e32 v4, v68
	v_mov_b32_e32 v5, v69
	v_lshlrev_b32_e32 v6, 16, v114
	v_fmac_f32_e32 v8, v6, v6
	v_lshlrev_b32_e32 v0, 16, v2
	v_fmac_f32_e32 v7, v6, v0
	v_and_b32_e32 v0, 0xffff0000, v114
	v_and_b32_e32 v2, 0xffff0000, v2
	v_fmac_f32_e32 v7, v0, v2
	v_fmac_f32_e32 v8, v0, v0
	v_lshlrev_b32_e32 v0, 16, v115
	v_lshlrev_b32_e32 v2, 16, v3
	v_fmac_f32_e32 v7, v0, v2
	v_fmac_f32_e32 v8, v0, v0
	v_and_b32_e32 v0, 0xffff0000, v115
	v_and_b32_e32 v2, 0xffff0000, v3
	v_fmac_f32_e32 v7, v0, v2
	v_fmac_f32_e32 v8, v0, v0
	v_lshlrev_b32_e32 v0, 16, v116
	v_lshlrev_b32_e32 v2, 16, v4
	v_fmac_f32_e32 v7, v0, v2
	v_fmac_f32_e32 v8, v0, v0
	v_and_b32_e32 v0, 0xffff0000, v116
	v_and_b32_e32 v2, 0xffff0000, v4
	v_fmac_f32_e32 v7, v0, v2
	v_fmac_f32_e32 v8, v0, v0
	v_lshlrev_b32_e32 v0, 16, v117
	v_lshlrev_b32_e32 v2, 16, v5
	v_fmac_f32_e32 v7, v0, v2
	v_fmac_f32_e32 v8, v0, v0
	v_and_b32_e32 v0, 0xffff0000, v117
	v_and_b32_e32 v2, 0xffff0000, v5
	v_fmac_f32_e32 v7, v0, v2
	s_waitcnt vmcnt(1)
	v_mov_b32_e32 v2, v70
	v_mov_b32_e32 v3, v71
	v_fmac_f32_e32 v8, v0, v0
	v_mov_b32_e32 v0, v7
	s_nop 1
	v_permlane32_swap_b32_e32 v7, v0
	v_add_f32_e32 v4, v7, v0
	v_mov_b32_e32 v0, v8
	s_nop 1
	v_permlane32_swap_b32_e32 v8, v0
	v_add_f32_e32 v0, v8, v0
	s_waitcnt vmcnt(1)
	v_add_f32_e32 v2, v2, v3
	v_cmp_gt_f32_e32 vcc, s3, v2
	v_mul_f32_e32 v3, 0x4f800000, v2
	s_nop 0
	v_cndmask_b32_e32 v2, v2, v3, vcc
	v_sqrt_f32_e32 v3, v2
	s_nop 0
	v_add_u32_e32 v5, -1, v3
	v_fma_f32 v6, -v5, v3, v2
	v_cmp_ge_f32_e64 s[6:7], 0, v6
	v_add_u32_e32 v6, 1, v3
	s_nop 0
	v_cndmask_b32_e64 v5, v3, v5, s[6:7]
	v_fma_f32 v3, -v6, v3, v2
	v_cmp_lt_f32_e64 s[6:7], 0, v3
	s_nop 1
	v_cndmask_b32_e64 v3, v5, v6, s[6:7]
	v_mul_f32_e32 v5, 0x37800000, v3
	v_cndmask_b32_e32 v3, v3, v5, vcc
	v_cmp_class_f32_e32 vcc, v2, v231
	s_nop 1
	v_cndmask_b32_e32 v5, v3, v2, vcc
	v_or_b32_e32 v2, s2, v190
	v_ashrrev_i32_e32 v3, 31, v2
	v_lshl_add_u64 v[2:3], v[2:3], 2, s[44:45]
	s_waitcnt vmcnt(0)
	v_mov_b32_e32 v2, v72
	v_cmp_gt_f32_e32 vcc, s3, v0
	v_mul_f32_e32 v3, 0x4f800000, v0
	s_waitcnt vmcnt(0)
	v_add_f32_e32 v2, v4, v2
	v_cndmask_b32_e32 v0, v0, v3, vcc
	v_sqrt_f32_e32 v3, v0
	s_nop 0
	v_add_u32_e32 v4, -1, v3
	v_fma_f32 v6, -v4, v3, v0
	v_cmp_ge_f32_e64 s[6:7], 0, v6
	v_add_u32_e32 v6, 1, v3
	s_nop 0
	v_cndmask_b32_e64 v4, v3, v4, s[6:7]
	v_fma_f32 v3, -v6, v3, v0
	v_cmp_lt_f32_e64 s[6:7], 0, v3
	s_nop 1
	v_cndmask_b32_e64 v3, v4, v6, s[6:7]
	v_mul_f32_e32 v4, 0x37800000, v3
	v_cndmask_b32_e32 v3, v3, v4, vcc
	v_cmp_class_f32_e32 vcc, v0, v231
	s_nop 1
	v_cndmask_b32_e32 v0, v3, v0, vcc
	v_mul_f32_e32 v0, v0, v5
	v_lshlrev_b32_e32 v3, 2, v188
	v_fmac_f32_e32 v2, 0xbf8020c5, v0
	v_xor_b32_e32 v0, 4, v3
	ds_bpermute_b32 v0, v0, v2
	v_cmp_eq_u32_e32 vcc, 0, v188
	s_waitcnt lgkmcnt(0)
	v_max_f32_e32 v0, v0, v0
	v_min_f32_e32 v0, v2, v0
	v_xor_b32_e32 v2, 8, v3
	ds_bpermute_b32 v2, v2, v0
	s_waitcnt lgkmcnt(0)
	v_max_f32_e32 v2, v2, v2
	v_min_f32_e32 v0, v0, v2
	v_xor_b32_e32 v2, 16, v3
	ds_bpermute_b32 v2, v2, v0
	s_waitcnt lgkmcnt(0)
	v_max_f32_e32 v2, v2, v2
	v_min_f32_e32 v0, v0, v2
	v_xor_b32_e32 v2, 32, v3
	ds_bpermute_b32 v2, v2, v0
	s_waitcnt lgkmcnt(0)
	v_max_f32_e32 v2, v2, v2
	v_min_f32_e32 v0, v0, v2
	v_xor_b32_e32 v2, 64, v3
	ds_bpermute_b32 v2, v2, v0
	s_and_saveexec_b64 s[6:7], vcc
	s_cbranch_execz .LBB0_563
	s_waitcnt lgkmcnt(0)
	v_max_f32_e32 v2, v2, v2
	v_max_f32_e32 v0, v0, v0
	v_min_f32_e32 v0, v0, v2
	v_mov_b32_e32 v2, s50
	ds_write_b32 v2, v0 offset:49152
; template<int THRL> __device__ __forceinline__ void attn_unit(int b,int h,int qb,const bf16*Q,const bf16*__restrict__ K,const bf16*__restrict__ V,bf16*O,const bf16*GF,const float*CBh,const unsigned*KN,const unsigned*QN,char*shm){
;     ...
;     asm volatile("s_waitcnt lgkmcnt(0)\n\ts_barrier":::"memory");
;     umin=wmin[0];
;     #pragma unroll
;     for(int w_=1;w_<NW;++w_)umin=fminf(umin,wmin[w_*64]); }
;   { const float cutoff=umin-0.01f-40.f; const int ntm4=(q0+QB)/KVBLK-4; int cnt=0;
;     for(int base=0;base<ntm4;base+=64){ const int tt=base+lane; const bool skip=(tt<ntm4)&&(CBh[64*tt+63]<cutoff); cnt+=__popcll(__ballot(skip)); }
;     t0=__builtin_amdgcn_readfirstlane(cnt)&~1; }
.LBB0_563:
	s_or_b64 exec, exec, s[6:7]
	s_waitcnt lgkmcnt(0)
	s_barrier
	s_mov_b32 s2, 0
	s_cmp_eq_u32 s48, 31
	v_lshlrev_b32_e32 v186, 8, v188
	s_cbranch_scc1 .LBB0_568
	s_waitcnt lgkmcnt(0)
	ds_read2st64_b32 v[2:3], v1 offset0:192 offset1:193
	ds_read2st64_b32 v[4:5], v1 offset0:194 offset1:195
	ds_read2st64_b32 v[6:7], v1 offset0:196 offset1:197
	ds_read2st64_b32 v[8:9], v1 offset0:198 offset1:199
	s_add_i32 s18, s94, s51
	s_waitcnt lgkmcnt(3)
	v_max_f32_e32 v0, v3, v3
	v_max_f32_e32 v2, v2, v2
	v_min_f32_e32 v0, v2, v0
	s_waitcnt lgkmcnt(2)
	v_min3_f32 v0, v0, v4, v5
	s_waitcnt lgkmcnt(1)
	v_min3_f32 v0, v0, v6, v7
	s_lshl_b64 s[6:7], s[18:19], 15
	s_waitcnt lgkmcnt(0)
	v_min3_f32 v0, v0, v8, v9
	s_add_u32 s6, s64, s6
	v_add_f32_e32 v0, 0xbc23d70a, v0
	v_mov_b32_e32 v187, v1
	s_addc_u32 s7, s65, s7
	v_add_f32_e32 v0, 0xc2200000, v0
	v_add_u32_e32 v2, s89, v186
	s_mov_b32 s18, 0
	s_branch .LBB0_566
.LBB0_565:
	s_or_b64 exec, exec, s[44:45]
	v_cndmask_b32_e64 v4, 0, 1, s[6:7]
	v_cmp_ne_u32_e32 vcc, 0, v4
	s_bcnt1_i32_b64 s44, vcc
	s_add_i32 s2, s2, s44
	s_add_i32 s18, s18, 64
	s_mov_b64 s[44:45], 0x4000
	s_cmp_ge_i32 s18, s40
	v_add_u32_e32 v2, 0x4000, v2
	s_cbranch_scc1 .LBB0_568
.LBB0_566:
	v_add_u32_e32 v4, s18, v188
	v_cmp_gt_i32_e32 vcc, s40, v4
	s_andn2_b64 s[6:7], s[6:7], exec
	s_and_saveexec_b64 s[44:45], vcc
	s_cbranch_execz .LBB0_565
	ds_read_b32 v4, v2 offset:252
	s_andn2_b64 s[6:7], s[6:7], exec
	s_waitcnt lgkmcnt(0)
	v_cmp_lt_f32_e32 vcc, v4, v0
	s_and_b64 s[46:47], vcc, exec
	s_or_b64 s[6:7], s[6:7], s[46:47]
	s_branch .LBB0_565
